# phases 4 and 5: half of the workgroups (blockIdx bit 3) run their split-K tail piece before the main tile, so one half's HBM-bound epilogue overlaps the other half's MFMA main loop
# speedup vs baseline: 1.0223x; 1.0095x over previous
.LBB0_1008:
	s_cmp_gt_i32 s84, 4
	s_cselect_b64 s[4:5], -1, 0
	s_cmp_lt_i32 s85, 5
	s_cselect_b64 s[6:7], -1, 0
	s_or_b64 s[4:5], s[4:5], s[6:7]
	s_and_b64 vcc, exec, s[4:5]
	s_cbranch_vccnz .LBB0_1080
	s_mov_b32 s98, 0
.Lmy_p4_top:
	s_waitcnt lgkmcnt(0)
	s_load_dwordx2 s[12:13], s[0:1], 0x88
	s_load_dwordx2 s[8:9], s[0:1], 0xb8
	v_mov_b32_e32 v10, v170
	s_cmpk_lt_i32 s2, 0x100
	s_cselect_b64 s[10:11], -1, 0
	s_cmpk_gt_i32 s2, 0xff
	v_readfirstlane_b32 s4, v10
	s_cbranch_scc1 .LBB0_1025
	s_cmp_lg_u32 s98, 0
	s_cbranch_scc1 .Lmy_p4_main
	s_bitcmp1_b32 s2, 3
	s_cbranch_scc0 .Lmy_p4_main
	s_mov_b32 s98, 1
	s_branch .LBB0_1025
.Lmy_p4_main:
	v_lshlrev_b32_e32 v0, 4, v10
	v_add_u32_e32 v1, 0x2000, v0
	v_ashrrev_i32_e32 v2, 31, v1
	v_lshrrev_b32_e32 v2, 22, v2
	v_add_u32_e32 v2, v1, v2
	v_ashrrev_i32_e32 v9, 10, v2
	v_lshlrev_b32_e32 v2, 5, v9
	v_and_b32_e32 v8, 32, v2
	v_mul_i32_i24_e32 v2, 0x400, v9
	v_sub_u32_e32 v1, v1, v2
	v_lshrrev_b32_e32 v2, 4, v1
	v_bitop3_b32 v1, v2, v1, 32 bitop3:0x6c
	v_ashrrev_i32_e32 v2, 31, v1
	v_lshrrev_b32_e32 v2, 26, v2
	v_add_u32_e32 v2, v1, v2
	v_ashrrev_i32_e32 v11, 6, v2
	v_and_b32_e32 v2, 0xc0, v2
	v_sub_u32_e32 v1, v1, v2
	v_mov_b32_e32 v2, 1
	v_lshlrev_b32_e32 v3, 3, v9
	v_ashrrev_i16_sdwa v1, v2, sext(v1) dst_sel:DWORD dst_unused:UNUSED_PAD src0_sel:DWORD src1_sel:BYTE_0
	v_and_b32_e32 v3, -16, v3
	v_bfe_i32 v12, v1, 0, 16
	v_add_u32_e32 v3, v11, v3
	s_movk_i32 s22, 0xc00
	v_add_u32_e32 v1, v8, v12
	v_lshlrev_b32_e32 v4, 11, v3
	v_mul_lo_u32 v3, v3, s22
	v_lshl_add_u32 v128, v1, 1, v4
	v_add_lshl_u32 v130, v1, v3, 1
	v_ashrrev_i32_e32 v1, 31, v10
	v_lshrrev_b32_e32 v1, 26, v1
	v_add_u32_e32 v1, v10, v1
	v_ashrrev_i32_e32 v14, 6, v1
	v_lshlrev_b32_e32 v1, 5, v14
	v_and_b32_e32 v13, 32, v1
	v_bfe_i32 v1, v10, 27, 1
	v_lshrrev_b32_e32 v1, 22, v1
	v_add_u32_e32 v1, v0, v1
	v_and_b32_e32 v1, 0xfffffc00, v1
	v_sub_u32_e32 v0, v0, v1
	v_lshrrev_b32_e32 v1, 4, v0
	v_bitop3_b32 v1, v1, v0, 32 bitop3:0x6c
	v_ashrrev_i32_e32 v0, 31, v0
	v_lshrrev_b32_e32 v0, 26, v0
	v_add_u32_e32 v0, v1, v0
	v_ashrrev_i32_e32 v16, 6, v0
	s_waitcnt lgkmcnt(0)
	s_add_u32 s3, s12, 0x1000
	v_mul_i32_i24_e32 v0, 64, v16
	s_addc_u32 s33, s13, 0
	s_ashr_i32 s6, s4, 6
	v_sub_u32_e32 v0, v1, v0
	v_lshlrev_b32_e32 v1, 3, v14
	s_and_b32 s64, s2, 3
	s_ashr_i32 s5, s4, 8
	s_lshl_b32 s50, s6, 10
	v_ashrrev_i16_sdwa v0, v2, sext(v0) dst_sel:DWORD dst_unused:UNUSED_PAD src0_sel:DWORD src1_sel:BYTE_0
	v_and_b32_e32 v1, -16, v1
	s_ashr_i32 s65, s2, 2
	s_lshl_b32 s12, s64, 19
	v_bfe_i32 v15, v0, 0, 16
	v_add_u32_e32 v1, v16, v1
	s_add_u32 s42, s8, s12
	v_add_u32_e32 v0, v13, v15
	v_lshlrev_b32_e32 v2, 11, v1
	s_addc_u32 s43, s9, 0
	s_add_i32 s51, s50, 0
	v_lshl_add_u32 v132, v0, 1, v2
	s_add_i32 m0, s51, 0x10000
	s_mul_i32 s14, s65, 0x180000
	global_load_lds_dwordx4 v132, s[42:43]
	s_add_i32 m0, s51, 0x12000
	s_add_u32 s12, s42, 0x40000
	global_load_lds_dwordx4 v128, s[42:43]
	s_addc_u32 s13, s43, 0
	s_add_i32 m0, s51, 0x14000
	s_mul_hi_i32 s7, s65, 0x180000
	global_load_lds_dwordx4 v132, s[12:13]
	s_add_i32 m0, s51, 0x16000
	s_add_u32 s40, s3, s14
	v_mul_lo_u32 v1, v1, s22
	s_addc_u32 s41, s33, s7
	s_add_i32 s52, s51, 0x2000
	v_add_lshl_u32 v134, v0, v1, 1
	global_load_lds_dwordx4 v128, s[12:13]
	s_mov_b32 m0, s51
	s_add_u32 s12, s40, 0xc0000
	global_load_lds_dwordx4 v134, s[40:41]
	s_mov_b32 m0, s52
	s_addc_u32 s13, s41, 0
	s_add_i32 s53, s51, 0x4000
	global_load_lds_dwordx4 v130, s[40:41]
	s_mov_b32 m0, s53
	s_add_i32 s54, s51, 0x6000
	global_load_lds_dwordx4 v134, s[12:13]
	s_mov_b32 m0, s54
	v_mov_b32_e32 v137, 0
	global_load_lds_dwordx4 v130, s[12:13]
	v_mov_b32_e32 v133, v137
	v_mov_b32_e32 v129, v137
	v_mov_b32_e32 v135, v137
	v_mov_b32_e32 v131, v137
	s_cmp_eq_u32 s5, 1
	s_mov_b32 s34, 0
	v_lshl_add_u64 v[6:7], s[42:43], 0, v[132:133]
	v_lshl_add_u64 v[2:3], s[42:43], 0, v[128:129]
	s_mov_b64 s[12:13], 0x40000
	v_lshl_add_u64 v[0:1], s[40:41], 0, v[134:135]
	s_cselect_b64 s[14:15], -1, 0
	s_cmp_lg_u32 s5, 1
	v_lshl_add_u64 v[4:5], s[40:41], 0, v[130:131]
	s_cbranch_scc1 .LBB0_1012
	s_barrier

.LBB0_1024:
	s_waitcnt vmcnt(0)
	s_barrier
	s_load_dwordx2 s[12:13], s[0:1], 0x88
	s_load_dwordx2 s[8:9], s[0:1], 0xb8
	s_cmp_eq_u32 s98, 2
	s_cbranch_scc1 .LBB0_1030

.LBB0_1027:
	s_ashr_i32 s9, s16, 5
	s_lshl_b32 s17, s9, 6
	s_and_b32 s8, s3, 0xc0
	s_and_b32 s17, s17, 0xffffff00
	s_or_b32 s8, s8, s17
	s_lshl_b32 s9, s9, 8
	v_add_u32_e32 v0, s8, v14
	s_and_b32 s18, s9, 0x300
	v_mad_i64_i32 v[10:11], s[8:9], v0, s15, v[6:7]
	s_lshl_b32 s8, s13, 11
	v_or_b32_e32 v0, s18, v16
	s_and_b32 s8, s8, 0x70000
	v_lshl_or_b32 v4, v0, 11, s8
	v_lshl_add_u64 v[12:13], v[8:9], 0, v[4:5]
	v_mov_b32_e32 v176, v12
	v_mov_b32_e32 v177, v13
	v_mov_b32_e32 v178, v10
	v_mov_b32_e32 v179, v11
	s_lshl_b32 s8, s16, 3
	s_and_b32 s8, s8, 0xc0
	s_lshl_b32 s9, s16, 5
	s_add_i32 s17, s17, s8
	s_and_b32 s9, s9, 0xe0
	v_add_u32_e32 v10, s17, v14
	s_or_b32 s9, s18, s9
	v_ashrrev_i32_e32 v11, 31, v10
	v_or_b32_e32 v4, s9, v15
	v_lshlrev_b64 v[10:11], 11, v[10:11]
	v_lshl_or_b32 v10, v4, 1, v10
	v_lshl_add_u64 v[12:13], s[4:5], 0, v[10:11]
	v_lshl_add_u64 v[18:19], s[6:7], 0, v[10:11]
	global_load_dwordx2 v[12:13], v[12:13], off
	global_load_dwordx2 v[18:19], v[18:19], off
	v_lshl_add_u64 v[10:11], s[10:11], 0, v[10:11]
	v_readfirstlane_b32 s20, v170
	s_nop 3
	s_lshr_b32 s20, s20, 6
	s_and_b32 s21, s20, 1
	s_lshr_b32 s22, s20, 1
	s_lshl_b32 s23, s20, 8
	s_lshl_b32 s28, s21, 15
	s_sub_u32 s24, s23, s28
	s_subb_u32 s25, 0, 0
	s_mul_i32 s28, s22, 98304
	s_add_u32 s29, s23, 4096
	s_sub_u32 s26, s29, s28
	s_subb_u32 s27, 0, 0
	v_lshl_add_u64 v[172:173], v[176:177], 0, s[24:25]
	v_lshl_add_u64 v[84:85], v[178:179], 0, s[26:27]
	s_mov_b64 s[28:29], 0x8000
	v_lshl_add_u64 v[174:175], v[172:173], 0, s[28:29]
	s_mov_b64 s[28:29], 98304
	v_lshl_add_u64 v[86:87], v[84:85], 0, s[28:29]
	v_lshl_add_u64 v[88:89], v[86:87], 0, s[28:29]
	v_lshl_add_u64 v[90:91], v[88:89], 0, s[28:29]
	global_load_dwordx4 v[20:23], v[84:85], off offset:0
	global_load_dwordx4 v[24:27], v[86:87], off offset:0
	global_load_dwordx4 v[28:31], v[88:89], off offset:0
	global_load_dwordx4 v[32:35], v[90:91], off offset:0
	global_load_dwordx4 v[36:39], v[172:173], off offset:0
	global_load_dwordx4 v[40:43], v[174:175], off offset:0
	global_load_dwordx4 v[44:47], v[84:85], off offset:64
	global_load_dwordx4 v[48:51], v[86:87], off offset:64
	global_load_dwordx4 v[52:55], v[88:89], off offset:64
	global_load_dwordx4 v[56:59], v[90:91], off offset:64
	global_load_dwordx4 v[60:63], v[172:173], off offset:64
	global_load_dwordx4 v[64:67], v[174:175], off offset:64
	global_load_dwordx4 v[68:71], v[84:85], off offset:128
	global_load_dwordx4 v[72:75], v[86:87], off offset:128
	global_load_dwordx4 v[76:79], v[88:89], off offset:128
	global_load_dwordx4 v[80:83], v[90:91], off offset:128
	global_load_dwordx4 v[92:95], v[172:173], off offset:128
	global_load_dwordx4 v[96:99], v[174:175], off offset:128
	global_load_dwordx4 v[100:103], v[84:85], off offset:192
	global_load_dwordx4 v[104:107], v[86:87], off offset:192
	global_load_dwordx4 v[108:111], v[88:89], off offset:192
	global_load_dwordx4 v[112:115], v[90:91], off offset:192
	global_load_dwordx4 v[116:119], v[172:173], off offset:192
	global_load_dwordx4 v[120:123], v[174:175], off offset:192
	v_mov_b32_e32 v124, 0
	v_mov_b32_e32 v125, 0
	v_mov_b32_e32 v126, 0
	v_mov_b32_e32 v127, 0
	v_mov_b32_e32 v128, 0
	v_mov_b32_e32 v129, 0
	v_mov_b32_e32 v130, 0
	v_mov_b32_e32 v131, 0
	v_mov_b32_e32 v132, 0
	v_mov_b32_e32 v133, 0
	v_mov_b32_e32 v134, 0
	v_mov_b32_e32 v135, 0
	v_mov_b32_e32 v136, 0
	v_mov_b32_e32 v137, 0
	v_mov_b32_e32 v138, 0
	v_mov_b32_e32 v139, 0
	v_mov_b32_e32 v140, 0
	v_mov_b32_e32 v141, 0
	v_mov_b32_e32 v142, 0
	v_mov_b32_e32 v143, 0
	v_mov_b32_e32 v144, 0
	v_mov_b32_e32 v145, 0
	v_mov_b32_e32 v146, 0
	v_mov_b32_e32 v147, 0
	v_mov_b32_e32 v148, 0
	v_mov_b32_e32 v149, 0
	v_mov_b32_e32 v150, 0
	v_mov_b32_e32 v151, 0
	v_mov_b32_e32 v152, 0
	v_mov_b32_e32 v153, 0
	v_mov_b32_e32 v154, 0
	v_mov_b32_e32 v155, 0
	v_and_b32_e32 v156, 63, v170
	v_lshlrev_b32_e32 v156, 4, v156
	s_lshl_b32 s28, s20, 10
	v_add_u32_e32 v157, s28, v156
	s_lshl_b32 s28, s20, 13
	v_add_u32_e32 v158, s28, v156
	s_waitcnt vmcnt(18)
	v_mfma_f32_16x16x32_bf16 v[124:127], v[36:39], v[20:23], v[124:127]
	v_mfma_f32_16x16x32_bf16 v[128:131], v[40:43], v[20:23], v[128:131]
	v_mfma_f32_16x16x32_bf16 v[132:135], v[36:39], v[24:27], v[132:135]
	v_mfma_f32_16x16x32_bf16 v[136:139], v[40:43], v[24:27], v[136:139]
	v_mfma_f32_16x16x32_bf16 v[140:143], v[36:39], v[28:31], v[140:143]
	v_mfma_f32_16x16x32_bf16 v[144:147], v[40:43], v[28:31], v[144:147]
	v_mfma_f32_16x16x32_bf16 v[148:151], v[36:39], v[32:35], v[148:151]
	v_mfma_f32_16x16x32_bf16 v[152:155], v[40:43], v[32:35], v[152:155]
	s_waitcnt vmcnt(12)
	v_mfma_f32_16x16x32_bf16 v[124:127], v[60:63], v[44:47], v[124:127]
	v_mfma_f32_16x16x32_bf16 v[128:131], v[64:67], v[44:47], v[128:131]
	v_mfma_f32_16x16x32_bf16 v[132:135], v[60:63], v[48:51], v[132:135]
	v_mfma_f32_16x16x32_bf16 v[136:139], v[64:67], v[48:51], v[136:139]
	v_mfma_f32_16x16x32_bf16 v[140:143], v[60:63], v[52:55], v[140:143]
	v_mfma_f32_16x16x32_bf16 v[144:147], v[64:67], v[52:55], v[144:147]
	v_mfma_f32_16x16x32_bf16 v[148:151], v[60:63], v[56:59], v[148:151]
	v_mfma_f32_16x16x32_bf16 v[152:155], v[64:67], v[56:59], v[152:155]
	s_waitcnt vmcnt(6)
	v_mfma_f32_16x16x32_bf16 v[124:127], v[92:95], v[68:71], v[124:127]
	v_mfma_f32_16x16x32_bf16 v[128:131], v[96:99], v[68:71], v[128:131]
	v_mfma_f32_16x16x32_bf16 v[132:135], v[92:95], v[72:75], v[132:135]
	v_mfma_f32_16x16x32_bf16 v[136:139], v[96:99], v[72:75], v[136:139]
	v_mfma_f32_16x16x32_bf16 v[140:143], v[92:95], v[76:79], v[140:143]
	v_mfma_f32_16x16x32_bf16 v[144:147], v[96:99], v[76:79], v[144:147]
	v_mfma_f32_16x16x32_bf16 v[148:151], v[92:95], v[80:83], v[148:151]
	v_mfma_f32_16x16x32_bf16 v[152:155], v[96:99], v[80:83], v[152:155]
	s_waitcnt vmcnt(0)
	v_mfma_f32_16x16x32_bf16 v[124:127], v[116:119], v[100:103], v[124:127]
	v_mfma_f32_16x16x32_bf16 v[128:131], v[120:123], v[100:103], v[128:131]
	v_mfma_f32_16x16x32_bf16 v[132:135], v[116:119], v[104:107], v[132:135]
	v_mfma_f32_16x16x32_bf16 v[136:139], v[120:123], v[104:107], v[136:139]
	v_mfma_f32_16x16x32_bf16 v[140:143], v[116:119], v[108:111], v[140:143]
	v_mfma_f32_16x16x32_bf16 v[144:147], v[120:123], v[108:111], v[144:147]
	v_mfma_f32_16x16x32_bf16 v[148:151], v[116:119], v[112:115], v[148:151]
	v_mfma_f32_16x16x32_bf16 v[152:155], v[120:123], v[112:115], v[152:155]
	s_nop 8
	ds_write_b128 v157, v[124:127] offset:0
	ds_write_b128 v157, v[128:131] offset:8192
	ds_write_b128 v157, v[132:135] offset:16384
	ds_write_b128 v157, v[136:139] offset:24576
	ds_write_b128 v157, v[140:143] offset:32768
	ds_write_b128 v157, v[144:147] offset:40960
	ds_write_b128 v157, v[148:151] offset:49152
	ds_write_b128 v157, v[152:155] offset:57344
	s_waitcnt lgkmcnt(0)
	s_barrier
	ds_read_b128 v[20:23], v158 offset:0
	ds_read_b128 v[24:27], v158 offset:1024
	ds_read_b128 v[28:31], v158 offset:2048
	ds_read_b128 v[32:35], v158 offset:3072
	ds_read_b128 v[36:39], v158 offset:4096
	ds_read_b128 v[40:43], v158 offset:5120
	ds_read_b128 v[44:47], v158 offset:6144
	ds_read_b128 v[48:51], v158 offset:7168
	s_waitcnt lgkmcnt(0)
	v_pk_add_f32 v[0:1], v[20:21], v[24:25]
	v_pk_add_f32 v[2:3], v[22:23], v[26:27]
	v_pk_add_f32 v[0:1], v[0:1], v[28:29]
	v_pk_add_f32 v[2:3], v[2:3], v[30:31]
	v_pk_add_f32 v[0:1], v[0:1], v[32:33]
	v_pk_add_f32 v[2:3], v[2:3], v[34:35]
	v_pk_add_f32 v[0:1], v[0:1], v[36:37]
	v_pk_add_f32 v[2:3], v[2:3], v[38:39]
	v_pk_add_f32 v[0:1], v[0:1], v[40:41]
	v_pk_add_f32 v[2:3], v[2:3], v[42:43]
	v_pk_add_f32 v[0:1], v[0:1], v[44:45]
	v_pk_add_f32 v[2:3], v[2:3], v[46:47]
	v_pk_add_f32 v[0:1], v[0:1], v[48:49]
	v_pk_add_f32 v[2:3], v[2:3], v[50:51]
	s_add_i32 s16, s16, s30
	s_add_i32 s3, s3, s12
	s_add_i32 s13, s13, s14
	s_cmpk_gt_i32 s16, 0xff
	s_waitcnt vmcnt(0)
	v_lshlrev_b32_e32 v20, 16, v12
	v_and_b32_e32 v21, 0xffff0000, v12
	v_lshlrev_b32_e32 v22, 16, v18
	v_and_b32_e32 v23, 0xffff0000, v18
	v_lshlrev_b32_e32 v12, 16, v13
	v_and_b32_e32 v13, 0xffff0000, v13
	v_lshlrev_b32_e32 v18, 16, v19
	v_and_b32_e32 v19, 0xffff0000, v19
	v_pk_fma_f32 v[0:1], v[0:1], v[22:23], v[20:21]
	v_pk_fma_f32 v[2:3], v[2:3], v[18:19], v[12:13]
	v_cvt_pk_bf16_f32 v0, v0, v1
	v_cvt_pk_bf16_f32 v1, v2, v3
	global_store_dwordx2 v[10:11], v[0:1], off
	s_cbranch_scc0 .LBB0_1027
	s_cmp_lg_u32 s98, 1
	s_cbranch_scc1 .LBB0_1030
	s_mov_b32 s98, 2
	s_waitcnt vmcnt(0) lgkmcnt(0)
	s_barrier
	s_branch .Lmy_p4_top

.LBB0_1080:
	s_cmp_gt_i32 s84, 5
	s_cselect_b64 s[4:5], -1, 0
	s_cmp_lt_i32 s85, 6
	s_cselect_b64 s[6:7], -1, 0
	s_or_b64 s[4:5], s[4:5], s[6:7]
	s_and_b64 vcc, exec, s[4:5]
	s_cbranch_vccnz .LBB0_1183
	s_mov_b32 s98, 0
.Lmy_p5_top:
	v_mov_b32_e32 v132, v170
	s_cmpk_lt_i32 s2, 0x100
	s_waitcnt lgkmcnt(0)
	s_cselect_b64 s[8:9], -1, 0
	s_cmpk_gt_i32 s2, 0xff
	v_readfirstlane_b32 s4, v132
	s_cbranch_scc1 .LBB0_1128
	s_cmp_lg_u32 s98, 0
	s_cbranch_scc1 .Lmy_p5_main
	s_bitcmp1_b32 s2, 3
	s_cbranch_scc0 .Lmy_p5_main
	s_mov_b32 s98, 1
	s_branch .LBB0_1128
.Lmy_p5_main:
	v_lshlrev_b32_e32 v160, 4, v132
	v_add_u32_e32 v0, 0x2000, v160
	v_ashrrev_i32_e32 v1, 31, v0
	v_lshrrev_b32_e32 v1, 22, v1
	v_add_u32_e32 v1, v0, v1
	v_ashrrev_i32_e32 v8, 10, v1
	v_mul_i32_i24_e32 v2, 0x400, v8
	v_sub_u32_e32 v0, v0, v2
	v_lshrrev_b32_e32 v2, 4, v0
	v_bitop3_b32 v0, v2, v0, 32 bitop3:0x6c
	v_ashrrev_i32_e32 v2, 31, v0
	v_lshrrev_b32_e32 v2, 26, v2
	v_add_u32_e32 v2, v0, v2
	v_ashrrev_i32_e32 v9, 6, v2
	v_and_b32_e32 v2, 0xc0, v2
	v_sub_u32_e32 v0, v0, v2
	v_mov_b32_e32 v2, 1
	v_lshlrev_b32_e32 v1, 5, v8
	v_ashrrev_i16_sdwa v0, v2, sext(v0) dst_sel:DWORD dst_unused:UNUSED_PAD src0_sel:DWORD src1_sel:BYTE_0
	v_and_b32_e32 v1, 32, v1
	v_bfe_i32 v10, v0, 0, 16
	v_add_u32_e32 v0, v1, v10
	v_lshlrev_b32_e32 v1, 3, v8
	v_and_b32_e32 v1, 0x1ffff0, v1
	v_add_lshl_u32 v1, v9, v1, 11
	v_lshl_add_u32 v136, v0, 1, v1
	v_bfe_i32 v1, v132, 27, 1
	v_lshrrev_b32_e32 v1, 22, v1
	v_add_u32_e32 v1, v160, v1
	v_and_b32_e32 v1, 0xfffffc00, v1
	v_sub_u32_e32 v1, v160, v1
	v_lshrrev_b32_e32 v3, 4, v1
	v_bitop3_b32 v3, v3, v1, 32 bitop3:0x6c
	v_ashrrev_i32_e32 v1, 31, v1
	v_lshrrev_b32_e32 v1, 26, v1
	v_add_u32_e32 v1, v3, v1
	s_load_dwordx2 s[12:13], s[0:1], 0xa0
	s_load_dwordx2 s[14:15], s[0:1], 0xc0
	v_ashrrev_i32_e32 v133, 31, v132
	v_ashrrev_i32_e32 v12, 6, v1
	v_lshrrev_b32_e32 v0, 26, v133
	v_mul_i32_i24_e32 v1, 64, v12
	s_ashr_i32 s10, s2, 2
	v_add_u32_e32 v0, v132, v0
	v_sub_u32_e32 v1, v3, v1
	s_ashr_i32 s6, s4, 6
	s_and_b32 s3, s2, 3
	v_ashrrev_i32_e32 v11, 6, v0
	v_ashrrev_i16_sdwa v1, v2, sext(v1) dst_sel:DWORD dst_unused:UNUSED_PAD src0_sel:DWORD src1_sel:BYTE_0
	s_ashr_i32 s11, s10, 31
	s_ashr_i32 s5, s4, 8
	s_lshl_b32 s33, s6, 10
	v_lshlrev_b32_e32 v0, 5, v11
	v_bfe_i32 v13, v1, 0, 16
	v_lshlrev_b32_e32 v1, 3, v11
	s_lshl_b64 s[16:17], s[10:11], 19
	s_lshl_b32 s7, s3, 19
	v_and_b32_e32 v0, 32, v0
	v_and_b32_e32 v1, 0x1ffff0, v1
	s_waitcnt lgkmcnt(0)
	s_add_u32 s36, s14, s7
	v_add_u32_e32 v0, v0, v13
	v_add_lshl_u32 v1, v12, v1, 11
	s_addc_u32 s37, s15, 0
	s_add_i32 s11, s33, 0
	v_lshl_add_u32 v138, v0, 1, v1
	s_add_i32 m0, s11, 0x10000
	v_mov_b32_e32 v81, 0
	global_load_lds_dwordx4 v138, s[36:37]
	s_add_i32 m0, s11, 0x12000
	s_add_u32 s18, s36, 0x40000
	global_load_lds_dwordx4 v136, s[36:37]
	s_addc_u32 s19, s37, 0
	s_add_i32 m0, s11, 0x14000
	v_mov_b32_e32 v139, v81
	global_load_lds_dwordx4 v138, s[18:19]
	s_add_i32 m0, s11, 0x16000
	s_add_u32 s42, s12, s16
	s_addc_u32 s43, s13, s17
	s_add_i32 s55, s11, 0x2000
	global_load_lds_dwordx4 v136, s[18:19]
	s_mov_b32 m0, s11
	s_add_u32 s16, s42, 0x40000
	global_load_lds_dwordx4 v138, s[42:43]
	s_mov_b32 m0, s55
	s_addc_u32 s17, s43, 0
	s_add_i32 s56, s11, 0x4000
	global_load_lds_dwordx4 v136, s[42:43]
	s_mov_b32 m0, s56
	s_add_i32 s57, s11, 0x6000
	global_load_lds_dwordx4 v138, s[16:17]
	s_mov_b32 m0, s57
	v_mov_b32_e32 v137, v81
	global_load_lds_dwordx4 v136, s[16:17]
	s_cmp_eq_u32 s5, 1
	v_lshl_add_u64 v[6:7], s[36:37], 0, v[138:139]
	v_lshl_add_u64 v[4:5], s[36:37], 0, v[136:137]
	v_lshl_add_u64 v[2:3], s[42:43], 0, v[138:139]
	v_lshl_add_u64 v[0:1], s[42:43], 0, v[136:137]
	s_cselect_b64 s[16:17], -1, 0
	s_cmp_lg_u32 s5, 1
	s_movk_i32 s58, 0x4000
	s_cbranch_scc1 .LBB0_1084
	s_barrier

.LBB0_1127:
	s_or_b64 exec, exec, s[6:7]
	s_waitcnt lgkmcnt(0)
	s_barrier
	s_load_dwordx2 s[10:11], s[0:1], 0x78
	s_load_dwordx4 s[4:7], s[0:1], 0x78
	v_lshlrev_b64 v[132:133], 2, v[136:137]
	s_add_i32 s3, 0, 0x21000
	v_lshl_add_u32 v139, v134, 2, s3
	s_waitcnt lgkmcnt(0)
	v_lshl_add_u64 v[136:137], s[10:11], 0, v[132:133]
	global_load_dwordx4 v[158:161], v[136:137], off
	global_load_dwordx4 v[162:165], v[136:137], off offset:16
	ds_read_b32 v134, v139
	s_load_dwordx2 s[10:11], s[0:1], 0x80
	s_add_u32 s6, s6, s12
	s_addc_u32 s7, s7, s13
	v_lshl_add_u32 v143, v154, 2, s3
	s_waitcnt lgkmcnt(0)
	v_pk_mul_f32 v[130:131], v[130:131], v[134:135] op_sel_hi:[1,0]
	v_pk_mul_f32 v[128:129], v[128:129], v[134:135] op_sel_hi:[1,0]
	v_pk_mul_f32 v[136:137], v[126:127], v[134:135] op_sel_hi:[1,0]
	v_pk_mul_f32 v[134:135], v[124:125], v[134:135] op_sel_hi:[1,0]
	v_lshl_add_u64 v[124:125], s[6:7], 0, v[80:81]
	v_lshl_add_u64 v[154:155], v[124:125], 0, v[132:133]
	s_waitcnt vmcnt(1)
	v_pk_mul_f32 v[126:127], v[160:161], v[130:131]
	v_pk_mul_f32 v[124:125], v[158:159], v[128:129]
	s_waitcnt vmcnt(0)
	v_pk_mul_f32 v[130:131], v[164:165], v[136:137]
	v_pk_mul_f32 v[128:129], v[162:163], v[134:135]
	global_store_dwordx4 v[154:155], v[124:127], off nt
	global_store_dwordx4 v[154:155], v[128:131], off offset:16 nt
	s_nop 1
	v_lshl_add_u32 v129, v138, 2, s3
	ds_read_b32 v128, v129
	v_lshl_add_u64 v[124:125], s[6:7], 0, v[118:119]
	v_lshl_add_u64 v[130:131], v[124:125], 0, v[132:133]
	s_waitcnt lgkmcnt(0)
	v_pk_mul_f32 v[114:115], v[114:115], v[128:129] op_sel_hi:[1,0]
	v_pk_mul_f32 v[124:125], v[140:141], v[128:129] op_sel_hi:[1,0]
	v_pk_mul_f32 v[126:127], v[160:161], v[114:115]
	v_pk_mul_f32 v[110:111], v[110:111], v[128:129] op_sel_hi:[1,0]
	v_pk_mul_f32 v[114:115], v[112:113], v[128:129] op_sel_hi:[1,0]
	v_pk_mul_f32 v[124:125], v[158:159], v[124:125]
	v_pk_mul_f32 v[112:113], v[164:165], v[110:111]
	v_pk_mul_f32 v[110:111], v[162:163], v[114:115]
	global_store_dwordx4 v[130:131], v[124:127], off nt
	global_store_dwordx4 v[130:131], v[110:113], off offset:16 nt
	v_lshl_add_u32 v115, v142, 2, s3
	ds_read_b32 v114, v115
	v_lshl_add_u64 v[110:111], s[6:7], 0, v[108:109]
	v_lshl_add_u64 v[124:125], v[110:111], 0, v[132:133]
	s_waitcnt lgkmcnt(0)
	v_pk_mul_f32 v[98:99], v[98:99], v[114:115] op_sel_hi:[1,0]
	v_pk_mul_f32 v[110:111], v[144:145], v[114:115] op_sel_hi:[1,0]
	v_pk_mul_f32 v[112:113], v[160:161], v[98:99]
	v_pk_mul_f32 v[94:95], v[94:95], v[114:115] op_sel_hi:[1,0]
	v_pk_mul_f32 v[98:99], v[96:97], v[114:115] op_sel_hi:[1,0]
	v_pk_mul_f32 v[110:111], v[158:159], v[110:111]
	v_pk_mul_f32 v[96:97], v[164:165], v[94:95]
	v_pk_mul_f32 v[94:95], v[162:163], v[98:99]
	global_store_dwordx4 v[124:125], v[110:113], off nt
	global_store_dwordx4 v[124:125], v[94:97], off offset:16 nt
	v_lshl_add_u32 v99, v146, 2, s3
	ds_read_b32 v98, v99
	v_lshl_add_u64 v[94:95], s[6:7], 0, v[92:93]
	v_lshl_add_u64 v[110:111], v[94:95], 0, v[132:133]
	s_waitcnt lgkmcnt(0)
	v_pk_mul_f32 v[78:79], v[78:79], v[98:99] op_sel_hi:[1,0]
	v_pk_mul_f32 v[94:95], v[148:149], v[98:99] op_sel_hi:[1,0]
	v_pk_mul_f32 v[96:97], v[160:161], v[78:79]
	v_pk_mul_f32 v[74:75], v[74:75], v[98:99] op_sel_hi:[1,0]
	v_pk_mul_f32 v[78:79], v[76:77], v[98:99] op_sel_hi:[1,0]
	v_pk_mul_f32 v[94:95], v[158:159], v[94:95]
	v_pk_mul_f32 v[76:77], v[164:165], v[74:75]
	v_pk_mul_f32 v[74:75], v[162:163], v[78:79]
	global_store_dwordx4 v[110:111], v[94:97], off nt
	global_store_dwordx4 v[110:111], v[74:77], off offset:16 nt
	ds_read_b32 v78, v143
	s_nop 0
	v_lshl_add_u64 v[74:75], s[6:7], 0, v[72:73]
	v_lshl_add_u64 v[94:95], v[74:75], 0, v[132:133]
	s_waitcnt lgkmcnt(0)
	v_pk_mul_f32 v[62:63], v[62:63], v[78:79] op_sel_hi:[1,0]
	v_pk_mul_f32 v[74:75], v[150:151], v[78:79] op_sel_hi:[1,0]
	v_pk_mul_f32 v[76:77], v[160:161], v[62:63]
	v_pk_mul_f32 v[58:59], v[58:59], v[78:79] op_sel_hi:[1,0]
	v_pk_mul_f32 v[62:63], v[60:61], v[78:79] op_sel_hi:[1,0]
	v_pk_mul_f32 v[74:75], v[158:159], v[74:75]
	v_pk_mul_f32 v[60:61], v[164:165], v[58:59]
	v_pk_mul_f32 v[58:59], v[162:163], v[62:63]
	global_store_dwordx4 v[94:95], v[74:77], off nt
	global_store_dwordx4 v[94:95], v[58:61], off offset:16 nt
	ds_read_b32 v62, v139 offset:576
	s_nop 0
	v_lshl_add_u64 v[58:59], s[6:7], 0, v[56:57]
	v_lshl_add_u64 v[74:75], v[58:59], 0, v[132:133]
	s_waitcnt lgkmcnt(0)
	v_pk_mul_f32 v[46:47], v[46:47], v[62:63] op_sel_hi:[1,0]
	v_pk_mul_f32 v[58:59], v[152:153], v[62:63] op_sel_hi:[1,0]
	v_pk_mul_f32 v[60:61], v[160:161], v[46:47]
	v_pk_mul_f32 v[42:43], v[42:43], v[62:63] op_sel_hi:[1,0]
	v_pk_mul_f32 v[46:47], v[44:45], v[62:63] op_sel_hi:[1,0]
	v_pk_mul_f32 v[58:59], v[158:159], v[58:59]
	v_pk_mul_f32 v[44:45], v[164:165], v[42:43]
	v_pk_mul_f32 v[42:43], v[162:163], v[46:47]
	global_store_dwordx4 v[74:75], v[58:61], off nt
	global_store_dwordx4 v[74:75], v[42:45], off offset:16 nt
	ds_read_b32 v46, v139 offset:640
	s_nop 0
	v_lshl_add_u64 v[42:43], s[6:7], 0, v[40:41]
	v_lshl_add_u64 v[58:59], v[42:43], 0, v[132:133]
	s_waitcnt lgkmcnt(0)
	v_pk_mul_f32 v[30:31], v[30:31], v[46:47] op_sel_hi:[1,0]
	v_pk_mul_f32 v[42:43], v[156:157], v[46:47] op_sel_hi:[1,0]
	v_pk_mul_f32 v[44:45], v[160:161], v[30:31]
	v_pk_mul_f32 v[26:27], v[26:27], v[46:47] op_sel_hi:[1,0]
	v_pk_mul_f32 v[30:31], v[28:29], v[46:47] op_sel_hi:[1,0]
	v_pk_mul_f32 v[42:43], v[158:159], v[42:43]
	v_pk_mul_f32 v[28:29], v[164:165], v[26:27]
	v_pk_mul_f32 v[26:27], v[162:163], v[30:31]
	global_store_dwordx4 v[58:59], v[42:45], off nt
	global_store_dwordx4 v[58:59], v[26:29], off offset:16 nt
	ds_read_b32 v26, v139 offset:704
	s_nop 0
	v_lshl_add_u64 v[28:29], s[6:7], 0, v[24:25]
	v_lshl_add_u64 v[28:29], v[28:29], 0, v[132:133]
	s_waitcnt lgkmcnt(0)
	v_pk_mul_f32 v[14:15], v[14:15], v[26:27] op_sel_hi:[1,0]
	v_pk_mul_f32 v[12:13], v[12:13], v[26:27] op_sel_hi:[1,0]
	v_pk_mul_f32 v[10:11], v[10:11], v[26:27] op_sel_hi:[1,0]
	v_pk_mul_f32 v[8:9], v[8:9], v[26:27] op_sel_hi:[1,0]
	v_pk_mul_f32 v[14:15], v[160:161], v[14:15]
	v_pk_mul_f32 v[12:13], v[158:159], v[12:13]
	v_pk_mul_f32 v[10:11], v[164:165], v[10:11]
	v_pk_mul_f32 v[8:9], v[162:163], v[8:9]
	global_store_dwordx4 v[28:29], v[12:15], off nt
	global_store_dwordx4 v[28:29], v[8:11], off offset:16 nt
	s_nop 0
	v_lshl_add_u64 v[12:13], s[4:5], 0, v[132:133]
	global_load_dwordx4 v[8:11], v[12:13], off offset:512
	s_nop 0
	global_load_dwordx4 v[12:15], v[12:13], off offset:528
	ds_read_b32 v26, v139
	s_add_u32 s4, s10, s12
	s_addc_u32 s5, s11, s13
	v_lshl_add_u64 v[28:29], s[4:5], 0, v[80:81]
	v_lshl_add_u64 v[30:31], v[28:29], 0, v[132:133]
	s_waitcnt lgkmcnt(0)
	v_pk_mul_f32 v[28:29], v[122:123], v[26:27] op_sel_hi:[1,0]
	v_pk_mul_f32 v[42:43], v[120:121], v[26:27] op_sel_hi:[1,0]
	v_pk_mul_f32 v[44:45], v[82:83], v[26:27] op_sel_hi:[1,0]
	v_pk_mul_f32 v[46:47], v[116:117], v[26:27] op_sel_hi:[1,0]
	s_waitcnt vmcnt(1)
	v_pk_mul_f32 v[28:29], v[10:11], v[28:29]
	v_pk_mul_f32 v[26:27], v[8:9], v[42:43]
	s_waitcnt vmcnt(0)
	v_pk_mul_f32 v[44:45], v[14:15], v[44:45]
	v_pk_mul_f32 v[42:43], v[12:13], v[46:47]
	global_store_dwordx4 v[30:31], v[26:29], off offset:512 nt
	global_store_dwordx4 v[30:31], v[42:45], off offset:528 nt
	ds_read_b32 v30, v129
	v_lshl_add_u64 v[26:27], s[4:5], 0, v[118:119]
	v_lshl_add_u64 v[42:43], v[26:27], 0, v[132:133]
	s_waitcnt lgkmcnt(0)
	v_pk_mul_f32 v[26:27], v[106:107], v[30:31] op_sel_hi:[1,0]
	v_pk_mul_f32 v[44:45], v[104:105], v[30:31] op_sel_hi:[1,0]
	v_pk_mul_f32 v[28:29], v[10:11], v[26:27]
	v_pk_mul_f32 v[26:27], v[8:9], v[44:45]
	global_store_dwordx4 v[42:43], v[26:29], off offset:512 nt
	s_nop 1
	v_pk_mul_f32 v[26:27], v[102:103], v[30:31] op_sel_hi:[1,0]
	v_pk_mul_f32 v[30:31], v[100:101], v[30:31] op_sel_hi:[1,0]
	v_pk_mul_f32 v[28:29], v[14:15], v[26:27]
	v_pk_mul_f32 v[26:27], v[12:13], v[30:31]
	global_store_dwordx4 v[42:43], v[26:29], off offset:528 nt
	ds_read_b32 v30, v115
	s_nop 0
	v_lshl_add_u64 v[26:27], s[4:5], 0, v[108:109]
	v_lshl_add_u64 v[42:43], v[26:27], 0, v[132:133]
	s_waitcnt lgkmcnt(0)
	v_pk_mul_f32 v[26:27], v[90:91], v[30:31] op_sel_hi:[1,0]
	v_pk_mul_f32 v[44:45], v[88:89], v[30:31] op_sel_hi:[1,0]
	v_pk_mul_f32 v[28:29], v[10:11], v[26:27]
	v_pk_mul_f32 v[26:27], v[8:9], v[44:45]
	global_store_dwordx4 v[42:43], v[26:29], off offset:512 nt
	s_nop 1
	v_pk_mul_f32 v[26:27], v[86:87], v[30:31] op_sel_hi:[1,0]
	v_pk_mul_f32 v[30:31], v[84:85], v[30:31] op_sel_hi:[1,0]
	v_pk_mul_f32 v[28:29], v[14:15], v[26:27]
	v_pk_mul_f32 v[26:27], v[12:13], v[30:31]
	global_store_dwordx4 v[42:43], v[26:29], off offset:528 nt
	ds_read_b32 v30, v99
	s_nop 0
	v_lshl_add_u64 v[26:27], s[4:5], 0, v[92:93]
	v_lshl_add_u64 v[42:43], v[26:27], 0, v[132:133]
	s_waitcnt lgkmcnt(0)
	v_pk_mul_f32 v[26:27], v[70:71], v[30:31] op_sel_hi:[1,0]
	v_pk_mul_f32 v[44:45], v[68:69], v[30:31] op_sel_hi:[1,0]
	v_pk_mul_f32 v[28:29], v[10:11], v[26:27]
	v_pk_mul_f32 v[26:27], v[8:9], v[44:45]
	global_store_dwordx4 v[42:43], v[26:29], off offset:512 nt
	s_nop 1
	v_pk_mul_f32 v[26:27], v[66:67], v[30:31] op_sel_hi:[1,0]
	v_pk_mul_f32 v[30:31], v[64:65], v[30:31] op_sel_hi:[1,0]
	v_pk_mul_f32 v[28:29], v[14:15], v[26:27]
	v_pk_mul_f32 v[26:27], v[12:13], v[30:31]
	global_store_dwordx4 v[42:43], v[26:29], off offset:528 nt
	ds_read_b32 v30, v143
	s_nop 0
	v_lshl_add_u64 v[26:27], s[4:5], 0, v[72:73]
	v_lshl_add_u64 v[42:43], v[26:27], 0, v[132:133]
	s_waitcnt lgkmcnt(0)
	v_pk_mul_f32 v[26:27], v[54:55], v[30:31] op_sel_hi:[1,0]
	v_pk_mul_f32 v[44:45], v[52:53], v[30:31] op_sel_hi:[1,0]
	v_pk_mul_f32 v[28:29], v[10:11], v[26:27]
	v_pk_mul_f32 v[26:27], v[8:9], v[44:45]
	global_store_dwordx4 v[42:43], v[26:29], off offset:512 nt
	s_nop 1
	v_pk_mul_f32 v[26:27], v[50:51], v[30:31] op_sel_hi:[1,0]
	v_pk_mul_f32 v[30:31], v[48:49], v[30:31] op_sel_hi:[1,0]
	v_pk_mul_f32 v[28:29], v[14:15], v[26:27]
	v_pk_mul_f32 v[26:27], v[12:13], v[30:31]
	global_store_dwordx4 v[42:43], v[26:29], off offset:528 nt
	ds_read_b32 v30, v139 offset:576
	s_nop 0
	v_lshl_add_u64 v[26:27], s[4:5], 0, v[56:57]
	v_lshl_add_u64 v[42:43], v[26:27], 0, v[132:133]
	s_waitcnt lgkmcnt(0)
	v_pk_mul_f32 v[26:27], v[38:39], v[30:31] op_sel_hi:[1,0]
	v_pk_mul_f32 v[36:37], v[36:37], v[30:31] op_sel_hi:[1,0]
	v_pk_mul_f32 v[28:29], v[10:11], v[26:27]
	v_pk_mul_f32 v[26:27], v[8:9], v[36:37]
	global_store_dwordx4 v[42:43], v[26:29], off offset:512 nt
	s_nop 1
	v_pk_mul_f32 v[26:27], v[34:35], v[30:31] op_sel_hi:[1,0]
	v_pk_mul_f32 v[30:31], v[32:33], v[30:31] op_sel_hi:[1,0]
	v_pk_mul_f32 v[28:29], v[14:15], v[26:27]
	v_pk_mul_f32 v[26:27], v[12:13], v[30:31]
	global_store_dwordx4 v[42:43], v[26:29], off offset:528 nt
	ds_read_b32 v26, v139 offset:640
	s_nop 0
	v_lshl_add_u64 v[28:29], s[4:5], 0, v[40:41]
	v_lshl_add_u64 v[28:29], v[28:29], 0, v[132:133]
	s_waitcnt lgkmcnt(0)
	v_pk_mul_f32 v[22:23], v[22:23], v[26:27] op_sel_hi:[1,0]
	v_pk_mul_f32 v[20:21], v[20:21], v[26:27] op_sel_hi:[1,0]
	v_pk_mul_f32 v[18:19], v[18:19], v[26:27] op_sel_hi:[1,0]
	v_pk_mul_f32 v[16:17], v[16:17], v[26:27] op_sel_hi:[1,0]
	v_pk_mul_f32 v[22:23], v[10:11], v[22:23]
	v_pk_mul_f32 v[20:21], v[8:9], v[20:21]
	v_pk_mul_f32 v[18:19], v[14:15], v[18:19]
	v_pk_mul_f32 v[16:17], v[12:13], v[16:17]
	global_store_dwordx4 v[28:29], v[20:23], off offset:512 nt
	global_store_dwordx4 v[28:29], v[16:19], off offset:528 nt
	ds_read_b32 v16, v139 offset:704
	s_nop 0
	v_lshl_add_u64 v[18:19], s[4:5], 0, v[24:25]
	v_lshl_add_u64 v[18:19], v[18:19], 0, v[132:133]
	s_waitcnt lgkmcnt(0)
	v_pk_mul_f32 v[6:7], v[6:7], v[16:17] op_sel_hi:[1,0]
	v_pk_mul_f32 v[4:5], v[4:5], v[16:17] op_sel_hi:[1,0]
	v_pk_mul_f32 v[2:3], v[2:3], v[16:17] op_sel_hi:[1,0]
	v_pk_mul_f32 v[0:1], v[0:1], v[16:17] op_sel_hi:[1,0]
	v_pk_mul_f32 v[6:7], v[10:11], v[6:7]
	v_pk_mul_f32 v[4:5], v[8:9], v[4:5]
	v_pk_mul_f32 v[2:3], v[14:15], v[2:3]
	v_pk_mul_f32 v[0:1], v[12:13], v[0:1]
	global_store_dwordx4 v[18:19], v[4:7], off offset:512 nt
	global_store_dwordx4 v[18:19], v[0:3], off offset:528 nt
	s_cmp_eq_u32 s98, 2
	s_cbranch_scc1 .LBB0_1133

.LBB0_1130:
	s_ashr_i32 s13, s18, 5
	s_lshl_b32 s19, s13, 6
	s_lshl_b32 s13, s13, 8
	s_and_b32 s12, s16, 0xc0
	s_and_b32 s20, s19, 0xffffff00
	s_and_b32 s19, s13, 0x300
	s_lshl_b32 s13, s14, 11
	v_or_b32_e32 v0, s19, v17
	s_and_b32 s13, s13, 0x70000
	s_or_b32 s12, s12, s20
	v_lshl_or_b32 v4, v0, 11, s13
	v_add_u32_e32 v0, s12, v18
	v_ashrrev_i32_e32 v1, 31, v0
	v_lshlrev_b64 v[0:1], 11, v[0:1]
	v_lshl_add_u64 v[10:11], v[6:7], 0, v[4:5]
	v_lshl_add_u64 v[12:13], v[8:9], 0, v[0:1]
	v_mov_b32_e32 v176, v10
	v_mov_b32_e32 v177, v11
	v_mov_b32_e32 v178, v12
	v_mov_b32_e32 v179, v13
	s_lshl_b32 s12, s18, 3
	s_and_b32 s12, s12, 0xc0
	s_add_i32 s20, s20, s12
	v_add_u32_e32 v4, s20, v15
	v_or_b32_e32 v10, v4, v14
	s_lshl_b32 s12, s18, 5
	v_ashrrev_i32_e32 v11, 31, v10
	s_and_b32 s12, s12, 0xe0
	v_lshlrev_b64 v[20:21], 12, v[10:11]
	s_or_b32 s12, s19, s12
	v_lshl_add_u64 v[12:13], s[6:7], 0, v[20:21]
	v_or_b32_e32 v19, s12, v16
	v_lshl_add_u64 v[10:11], s[4:5], 0, v[20:21]
	v_lshl_add_u64 v[12:13], v[12:13], 0, s[10:11]
	v_cmp_gt_u32_e32 vcc, s3, v4
	v_lshlrev_b32_e32 v4, 2, v19
	s_nop 1
	v_cndmask_b32_e32 v11, v13, v11, vcc
	v_cndmask_b32_e32 v10, v12, v10, vcc
	v_lshl_add_u64 v[10:11], v[10:11], 0, v[4:5]
	global_load_dwordx4 v[10:13], v[10:11], off
	v_lshl_add_u64 v[20:21], s[8:9], 0, v[20:21]
	v_lshl_add_u64 v[20:21], v[20:21], 0, v[4:5]
	v_readfirstlane_b32 s88, v170
	s_nop 3
	s_lshr_b32 s88, s88, 6
	s_and_b32 s89, s88, 1
	s_lshr_b32 s90, s88, 1
	s_lshl_b32 s91, s88, 8
	s_lshl_b32 s96, s89, 15
	s_sub_u32 s92, s91, s96
	s_subb_u32 s93, 0, 0
	s_mul_i32 s96, s90, 32768
	s_add_u32 s97, s91, 0
	s_sub_u32 s94, s97, s96
	s_subb_u32 s95, 0, 0
	v_lshl_add_u64 v[172:173], v[176:177], 0, s[92:93]
	v_lshl_add_u64 v[84:85], v[178:179], 0, s[94:95]
	s_mov_b64 s[96:97], 0x8000
	v_lshl_add_u64 v[174:175], v[172:173], 0, s[96:97]
	s_mov_b64 s[96:97], 32768
	v_lshl_add_u64 v[86:87], v[84:85], 0, s[96:97]
	v_lshl_add_u64 v[88:89], v[86:87], 0, s[96:97]
	v_lshl_add_u64 v[90:91], v[88:89], 0, s[96:97]
	global_load_dwordx4 v[24:27], v[84:85], off offset:0
	global_load_dwordx4 v[28:31], v[86:87], off offset:0
	global_load_dwordx4 v[32:35], v[88:89], off offset:0
	global_load_dwordx4 v[36:39], v[90:91], off offset:0
	global_load_dwordx4 v[40:43], v[172:173], off offset:0
	global_load_dwordx4 v[44:47], v[174:175], off offset:0
	global_load_dwordx4 v[48:51], v[84:85], off offset:64
	global_load_dwordx4 v[52:55], v[86:87], off offset:64
	global_load_dwordx4 v[56:59], v[88:89], off offset:64
	global_load_dwordx4 v[60:63], v[90:91], off offset:64
	global_load_dwordx4 v[64:67], v[172:173], off offset:64
	global_load_dwordx4 v[68:71], v[174:175], off offset:64
	global_load_dwordx4 v[72:75], v[84:85], off offset:128
	global_load_dwordx4 v[76:79], v[86:87], off offset:128
	global_load_dwordx4 v[80:83], v[88:89], off offset:128
	global_load_dwordx4 v[92:95], v[90:91], off offset:128
	global_load_dwordx4 v[96:99], v[172:173], off offset:128
	global_load_dwordx4 v[100:103], v[174:175], off offset:128
	global_load_dwordx4 v[104:107], v[84:85], off offset:192
	global_load_dwordx4 v[108:111], v[86:87], off offset:192
	global_load_dwordx4 v[112:115], v[88:89], off offset:192
	global_load_dwordx4 v[116:119], v[90:91], off offset:192
	global_load_dwordx4 v[120:123], v[172:173], off offset:192
	global_load_dwordx4 v[124:127], v[174:175], off offset:192
	v_mov_b32_e32 v128, 0
	v_mov_b32_e32 v129, 0
	v_mov_b32_e32 v130, 0
	v_mov_b32_e32 v131, 0
	v_mov_b32_e32 v132, 0
	v_mov_b32_e32 v133, 0
	v_mov_b32_e32 v134, 0
	v_mov_b32_e32 v135, 0
	v_mov_b32_e32 v136, 0
	v_mov_b32_e32 v137, 0
	v_mov_b32_e32 v138, 0
	v_mov_b32_e32 v139, 0
	v_mov_b32_e32 v140, 0
	v_mov_b32_e32 v141, 0
	v_mov_b32_e32 v142, 0
	v_mov_b32_e32 v143, 0
	v_mov_b32_e32 v144, 0
	v_mov_b32_e32 v145, 0
	v_mov_b32_e32 v146, 0
	v_mov_b32_e32 v147, 0
	v_mov_b32_e32 v148, 0
	v_mov_b32_e32 v149, 0
	v_mov_b32_e32 v150, 0
	v_mov_b32_e32 v151, 0
	v_mov_b32_e32 v152, 0
	v_mov_b32_e32 v153, 0
	v_mov_b32_e32 v154, 0
	v_mov_b32_e32 v155, 0
	v_mov_b32_e32 v156, 0
	v_mov_b32_e32 v157, 0
	v_mov_b32_e32 v158, 0
	v_mov_b32_e32 v159, 0
	v_and_b32_e32 v160, 63, v170
	v_lshlrev_b32_e32 v160, 4, v160
	s_lshl_b32 s96, s88, 10
	v_add_u32_e32 v161, s96, v160
	s_lshl_b32 s96, s88, 13
	v_add_u32_e32 v162, s96, v160
	s_waitcnt vmcnt(18)
	v_mfma_f32_16x16x32_bf16 v[128:131], v[40:43], v[24:27], v[128:131]
	v_mfma_f32_16x16x32_bf16 v[132:135], v[44:47], v[24:27], v[132:135]
	v_mfma_f32_16x16x32_bf16 v[136:139], v[40:43], v[28:31], v[136:139]
	v_mfma_f32_16x16x32_bf16 v[140:143], v[44:47], v[28:31], v[140:143]
	v_mfma_f32_16x16x32_bf16 v[144:147], v[40:43], v[32:35], v[144:147]
	v_mfma_f32_16x16x32_bf16 v[148:151], v[44:47], v[32:35], v[148:151]
	v_mfma_f32_16x16x32_bf16 v[152:155], v[40:43], v[36:39], v[152:155]
	v_mfma_f32_16x16x32_bf16 v[156:159], v[44:47], v[36:39], v[156:159]
	s_waitcnt vmcnt(12)
	v_mfma_f32_16x16x32_bf16 v[128:131], v[64:67], v[48:51], v[128:131]
	v_mfma_f32_16x16x32_bf16 v[132:135], v[68:71], v[48:51], v[132:135]
	v_mfma_f32_16x16x32_bf16 v[136:139], v[64:67], v[52:55], v[136:139]
	v_mfma_f32_16x16x32_bf16 v[140:143], v[68:71], v[52:55], v[140:143]
	v_mfma_f32_16x16x32_bf16 v[144:147], v[64:67], v[56:59], v[144:147]
	v_mfma_f32_16x16x32_bf16 v[148:151], v[68:71], v[56:59], v[148:151]
	v_mfma_f32_16x16x32_bf16 v[152:155], v[64:67], v[60:63], v[152:155]
	v_mfma_f32_16x16x32_bf16 v[156:159], v[68:71], v[60:63], v[156:159]
	s_waitcnt vmcnt(6)
	v_mfma_f32_16x16x32_bf16 v[128:131], v[96:99], v[72:75], v[128:131]
	v_mfma_f32_16x16x32_bf16 v[132:135], v[100:103], v[72:75], v[132:135]
	v_mfma_f32_16x16x32_bf16 v[136:139], v[96:99], v[76:79], v[136:139]
	v_mfma_f32_16x16x32_bf16 v[140:143], v[100:103], v[76:79], v[140:143]
	v_mfma_f32_16x16x32_bf16 v[144:147], v[96:99], v[80:83], v[144:147]
	v_mfma_f32_16x16x32_bf16 v[148:151], v[100:103], v[80:83], v[148:151]
	v_mfma_f32_16x16x32_bf16 v[152:155], v[96:99], v[92:95], v[152:155]
	v_mfma_f32_16x16x32_bf16 v[156:159], v[100:103], v[92:95], v[156:159]
	s_waitcnt vmcnt(0)
	v_mfma_f32_16x16x32_bf16 v[128:131], v[120:123], v[104:107], v[128:131]
	v_mfma_f32_16x16x32_bf16 v[132:135], v[124:127], v[104:107], v[132:135]
	v_mfma_f32_16x16x32_bf16 v[136:139], v[120:123], v[108:111], v[136:139]
	v_mfma_f32_16x16x32_bf16 v[140:143], v[124:127], v[108:111], v[140:143]
	v_mfma_f32_16x16x32_bf16 v[144:147], v[120:123], v[112:115], v[144:147]
	v_mfma_f32_16x16x32_bf16 v[148:151], v[124:127], v[112:115], v[148:151]
	v_mfma_f32_16x16x32_bf16 v[152:155], v[120:123], v[116:119], v[152:155]
	v_mfma_f32_16x16x32_bf16 v[156:159], v[124:127], v[116:119], v[156:159]
	s_nop 8
	ds_write_b128 v161, v[128:131] offset:0
	ds_write_b128 v161, v[132:135] offset:8192
	ds_write_b128 v161, v[136:139] offset:16384
	ds_write_b128 v161, v[140:143] offset:24576
	ds_write_b128 v161, v[144:147] offset:32768
	ds_write_b128 v161, v[148:151] offset:40960
	ds_write_b128 v161, v[152:155] offset:49152
	ds_write_b128 v161, v[156:159] offset:57344
	s_waitcnt lgkmcnt(0)
	s_barrier
	ds_read_b128 v[24:27], v162 offset:0
	ds_read_b128 v[28:31], v162 offset:1024
	ds_read_b128 v[32:35], v162 offset:2048
	ds_read_b128 v[36:39], v162 offset:3072
	ds_read_b128 v[40:43], v162 offset:4096
	ds_read_b128 v[44:47], v162 offset:5120
	ds_read_b128 v[48:51], v162 offset:6144
	ds_read_b128 v[52:55], v162 offset:7168
	s_waitcnt lgkmcnt(0)
	v_pk_add_f32 v[0:1], v[24:25], v[28:29]
	v_pk_add_f32 v[2:3], v[26:27], v[30:31]
	v_pk_add_f32 v[0:1], v[0:1], v[32:33]
	v_pk_add_f32 v[2:3], v[2:3], v[34:35]
	v_pk_add_f32 v[0:1], v[0:1], v[36:37]
	v_pk_add_f32 v[2:3], v[2:3], v[38:39]
	v_pk_add_f32 v[0:1], v[0:1], v[40:41]
	v_pk_add_f32 v[2:3], v[2:3], v[42:43]
	v_pk_add_f32 v[0:1], v[0:1], v[44:45]
	v_pk_add_f32 v[2:3], v[2:3], v[46:47]
	v_pk_add_f32 v[0:1], v[0:1], v[48:49]
	v_pk_add_f32 v[2:3], v[2:3], v[50:51]
	v_pk_add_f32 v[0:1], v[0:1], v[52:53]
	v_pk_add_f32 v[2:3], v[2:3], v[54:55]
	s_add_i32 s18, s18, s30
	s_add_i32 s14, s14, s15
	s_add_i32 s16, s16, s17
	s_cmpk_gt_i32 s18, 0xff
	s_waitcnt vmcnt(0)
	v_pk_add_f32 v[2:3], v[2:3], v[12:13]
	v_pk_add_f32 v[0:1], v[0:1], v[10:11]
	global_store_dwordx4 v[20:21], v[0:3], off
	s_cbranch_scc0 .LBB0_1130
	s_cmp_lg_u32 s98, 1
	s_cbranch_scc1 .LBB0_1133
	s_mov_b32 s98, 2
	s_waitcnt vmcnt(0) lgkmcnt(0)
	s_barrier
	s_branch .Lmy_p5_top
